# speedup vs baseline: 1.0069x; 1.0069x over previous
.LBB0_156:
	s_ashr_i32 s3, s45, 8
	s_lshl_b32 s3, 1, s3
	v_and_b32_e32 v110, s3, v126
	v_cmp_eq_u32_e32 vcc, 0, v110
	v_max_f32_e32 v110, v163, v163
	v_max_f32_e32 v111, v164, v164
	v_max_f32_e32 v110, v111, v110
	v_max3_f32 v110, v110, v162, v161
	v_max3_f32 v110, v110, v160, v159
	v_max3_f32 v110, v110, v158, v157
	v_max3_f32 v110, v110, v147, v146
	v_max3_f32 v110, v110, v145, v144
	v_max3_f32 v110, v110, v143, v142
	v_max3_f32 v110, v110, v141, v140
	s_and_b64 s[4:5], s[60:61], vcc
	v_cndmask_b32_e64 v110, v110, v152, s[4:5]
	v_mov_b32_e32 v111, v110
	v_add_u32_e32 v112, s53, v101
	v_subrev_u32_e32 v112, 63, v112
	v_cvt_f32_i32_e32 v112, v112
	s_waitcnt lgkmcnt(4)
	ds_read_b128 v[218:221], v138 offset:46080
	ds_read_b128 v[222:225], v138 offset:46144
	ds_read_b128 v[226:229], v138 offset:50688
	ds_read_b128 v[230:233], v138 offset:50752
	v_permlane16_swap_b32_e32 v111, v110
	v_max_f32_e32 v110, v110, v111
	v_mov_b32_e32 v111, v110
	s_nop 1
	v_permlane32_swap_b32_e32 v111, v110
	v_max_f32_e32 v110, v110, v111
	v_fmac_f32_e32 v110, v68, v112
	v_max_f32_e32 v111, v139, v139
	v_max_f32_e32 v111, v111, v110
	v_sub_f32_e32 v110, v139, v111
	v_exp_f32_e32 v110, v110
	s_nop 0
	v_cmp_neq_f32_e32 vcc, 1.0, v110
	s_cbranch_vccz .LBB0_158
	v_pk_mul_f32 v[58:59], v[58:59], v[110:111] op_sel_hi:[1,0]
	v_pk_mul_f32 v[56:57], v[56:57], v[110:111] op_sel_hi:[1,0]
	v_pk_mul_f32 v[62:63], v[62:63], v[110:111] op_sel_hi:[1,0]
	v_pk_mul_f32 v[60:61], v[60:61], v[110:111] op_sel_hi:[1,0]
	v_pk_mul_f32 v[54:55], v[54:55], v[110:111] op_sel_hi:[1,0]
	v_pk_mul_f32 v[52:53], v[52:53], v[110:111] op_sel_hi:[1,0]
	v_pk_mul_f32 v[50:51], v[50:51], v[110:111] op_sel_hi:[1,0]
	v_pk_mul_f32 v[48:49], v[48:49], v[110:111] op_sel_hi:[1,0]
	v_pk_mul_f32 v[46:47], v[46:47], v[110:111] op_sel_hi:[1,0]
	v_pk_mul_f32 v[44:45], v[44:45], v[110:111] op_sel_hi:[1,0]
	v_pk_mul_f32 v[42:43], v[42:43], v[110:111] op_sel_hi:[1,0]
	v_pk_mul_f32 v[40:41], v[40:41], v[110:111] op_sel_hi:[1,0]
	v_pk_mul_f32 v[38:39], v[38:39], v[110:111] op_sel_hi:[1,0]
	v_pk_mul_f32 v[36:37], v[36:37], v[110:111] op_sel_hi:[1,0]
	v_pk_mul_f32 v[34:35], v[34:35], v[110:111] op_sel_hi:[1,0]
	v_pk_mul_f32 v[32:33], v[32:33], v[110:111] op_sel_hi:[1,0]
